# v20 plus removal of the per-MFMA-cluster s_setprio toggles in the three GEMM K-loops
# speedup vs baseline: 1.0110x; 1.0110x over previous
.LBB0_204:
	s_add_u32 s44, s40, 0xfff80080
	s_addc_u32 s45, s41, -1
	s_and_b64 s[4:5], s[42:43], exec
	s_cselect_b32 s45, s31, s45
	s_cselect_b32 s44, s65, s44
	s_add_i32 s70, 0, 0x10000
	v_add_u32_e32 v168, s70, v145
	ds_read_b128 v[156:159], v168
	ds_read_b128 v[160:163], v168 offset:1024
	ds_read_b128 v[164:167], v168 offset:2048
	ds_read_b128 v[168:171], v168 offset:3072
	s_and_b64 s[4:5], s[42:43], exec
	s_cselect_b32 s5, s29, s68
	s_cselect_b32 s4, s66, s67
	v_lshl_add_u64 v[176:177], s[40:41], 0, v[136:137]
	s_add_i32 m0, s39, 0xc000
	ds_read_b128 v[172:175], v147
	ds_read_b128 v[180:183], v147 offset:1024
	ds_read_b128 v[184:187], v147 offset:2048
	ds_read_b128 v[188:191], v147 offset:3072
	ds_read_b128 v[192:195], v147 offset:4096
	ds_read_b128 v[216:219], v147 offset:5120
	ds_read_b128 v[220:223], v147 offset:6144
	ds_read_b128 v[224:227], v147 offset:7168
	global_load_lds_dwordx4 v[176:177], off
	v_lshl_add_u64 v[176:177], s[40:41], 0, v[138:139]
	s_add_i32 m0, s39, 0xe000
	s_nop 0
	global_load_lds_dwordx4 v[176:177], off
	s_waitcnt lgkmcnt(8)
	s_barrier
	s_waitcnt lgkmcnt(0)
	s_waitcnt lgkmcnt(0)
	v_mfma_f32_16x16x32_bf16 v[126:129], v[156:159], v[172:175], v[126:129]
	v_mfma_f32_16x16x32_bf16 v[122:125], v[164:167], v[172:175], v[122:125]
	v_mfma_f32_16x16x32_bf16 v[110:113], v[156:159], v[184:187], v[110:113]
	v_mfma_f32_16x16x32_bf16 v[106:109], v[164:167], v[184:187], v[106:109]
	v_mfma_f32_16x16x32_bf16 v[94:97], v[156:159], v[192:195], v[94:97]
	v_mfma_f32_16x16x32_bf16 v[90:93], v[164:167], v[192:195], v[90:93]
	v_mfma_f32_16x16x32_bf16 v[78:81], v[156:159], v[220:223], v[78:81]
	v_mfma_f32_16x16x32_bf16 v[74:77], v[164:167], v[220:223], v[74:77]
	v_mfma_f32_16x16x32_bf16 v[126:129], v[160:163], v[180:183], v[126:129]
	v_mfma_f32_16x16x32_bf16 v[122:125], v[168:171], v[180:183], v[122:125]
	v_mfma_f32_16x16x32_bf16 v[110:113], v[160:163], v[188:191], v[110:113]
	v_mfma_f32_16x16x32_bf16 v[106:109], v[168:171], v[188:191], v[106:109]
	v_mfma_f32_16x16x32_bf16 v[94:97], v[160:163], v[216:219], v[94:97]
	v_mfma_f32_16x16x32_bf16 v[90:93], v[168:171], v[216:219], v[90:93]
	v_mfma_f32_16x16x32_bf16 v[78:81], v[160:163], v[224:227], v[78:81]
	v_mfma_f32_16x16x32_bf16 v[74:77], v[168:171], v[224:227], v[74:77]
	s_barrier
	s_add_i32 s71, 0, 0x14000
	v_add_u32_e32 v176, s71, v145
	s_add_i32 s42, s70, s56
	ds_read_b128 v[228:231], v176
	ds_read_b128 v[232:235], v176 offset:1024
	ds_read_b128 v[236:239], v176 offset:2048
	ds_read_b128 v[240:243], v176 offset:3072
	v_lshl_add_u64 v[176:177], s[4:5], 0, v[0:1]
	s_mov_b32 m0, s42
	v_lshl_add_u64 v[196:197], s[4:5], 0, v[134:135]
	global_load_lds_dwordx4 v[176:177], off
	s_add_i32 m0, s42, 0x2000
	s_nop 0
	global_load_lds_dwordx4 v[196:197], off
	s_barrier
	s_waitcnt lgkmcnt(0)
	s_waitcnt lgkmcnt(0)
	v_mfma_f32_16x16x32_bf16 v[118:121], v[228:231], v[172:175], v[118:121]
	v_mfma_f32_16x16x32_bf16 v[114:117], v[236:239], v[172:175], v[114:117]
	v_mfma_f32_16x16x32_bf16 v[102:105], v[228:231], v[184:187], v[102:105]
	v_mfma_f32_16x16x32_bf16 v[98:101], v[236:239], v[184:187], v[98:101]
	v_mfma_f32_16x16x32_bf16 v[86:89], v[228:231], v[192:195], v[86:89]
	v_mfma_f32_16x16x32_bf16 v[82:85], v[236:239], v[192:195], v[82:85]
	v_mfma_f32_16x16x32_bf16 v[70:73], v[228:231], v[220:223], v[70:73]
	v_mfma_f32_16x16x32_bf16 v[66:69], v[236:239], v[220:223], v[66:69]
	v_mfma_f32_16x16x32_bf16 v[118:121], v[232:235], v[180:183], v[118:121]
	v_mfma_f32_16x16x32_bf16 v[114:117], v[240:243], v[180:183], v[114:117]
	v_mfma_f32_16x16x32_bf16 v[102:105], v[232:235], v[188:191], v[102:105]
	v_mfma_f32_16x16x32_bf16 v[98:101], v[240:243], v[188:191], v[98:101]
	v_mfma_f32_16x16x32_bf16 v[86:89], v[232:235], v[216:219], v[86:89]
	v_mfma_f32_16x16x32_bf16 v[82:85], v[240:243], v[216:219], v[82:85]
	v_mfma_f32_16x16x32_bf16 v[70:73], v[232:235], v[224:227], v[70:73]
	v_mfma_f32_16x16x32_bf16 v[66:69], v[240:243], v[224:227], v[66:69]
	s_mov_b32 m0, s39
	v_lshl_add_u64 v[200:201], s[44:45], 0, v[130:131]
	s_barrier
	ds_read_b128 v[172:175], v147 offset:16384
	ds_read_b128 v[180:183], v147 offset:17408
	ds_read_b128 v[184:187], v147 offset:18432
	ds_read_b128 v[188:191], v147 offset:19456
	ds_read_b128 v[192:195], v147 offset:20480
	ds_read_b128 v[216:219], v147 offset:21504
	ds_read_b128 v[220:223], v147 offset:22528
	ds_read_b128 v[224:227], v147 offset:23552
	global_load_lds_dwordx4 v[200:201], off
	v_lshl_add_u64 v[206:207], s[44:45], 0, v[132:133]
	s_mov_b32 m0, s59
	s_nop 0
	global_load_lds_dwordx4 v[206:207], off
	s_barrier
	s_waitcnt lgkmcnt(0)
	s_waitcnt lgkmcnt(0)
	v_mfma_f32_16x16x32_bf16 v[62:65], v[156:159], v[172:175], v[62:65]
	v_mfma_f32_16x16x32_bf16 v[58:61], v[164:167], v[172:175], v[58:61]
	v_mfma_f32_16x16x32_bf16 v[46:49], v[156:159], v[184:187], v[46:49]
	v_mfma_f32_16x16x32_bf16 v[42:45], v[164:167], v[184:187], v[42:45]
	v_mfma_f32_16x16x32_bf16 v[30:33], v[156:159], v[192:195], v[30:33]
	v_mfma_f32_16x16x32_bf16 v[26:29], v[164:167], v[192:195], v[26:29]
	v_mfma_f32_16x16x32_bf16 v[14:17], v[156:159], v[220:223], v[14:17]
	v_mfma_f32_16x16x32_bf16 v[10:13], v[164:167], v[220:223], v[10:13]
	v_mfma_f32_16x16x32_bf16 v[62:65], v[160:163], v[180:183], v[62:65]
	v_mfma_f32_16x16x32_bf16 v[58:61], v[168:171], v[180:183], v[58:61]
	v_mfma_f32_16x16x32_bf16 v[46:49], v[160:163], v[188:191], v[46:49]
	v_mfma_f32_16x16x32_bf16 v[42:45], v[168:171], v[188:191], v[42:45]
	v_mfma_f32_16x16x32_bf16 v[30:33], v[160:163], v[216:219], v[30:33]
	v_mfma_f32_16x16x32_bf16 v[26:29], v[168:171], v[216:219], v[26:29]
	v_mfma_f32_16x16x32_bf16 v[14:17], v[160:163], v[224:227], v[14:17]
	v_mfma_f32_16x16x32_bf16 v[10:13], v[168:171], v[224:227], v[10:13]
	s_barrier
	s_add_u32 s42, s4, 0x80000
	s_addc_u32 s43, s5, 0
	s_add_i32 s70, s71, s56
	v_lshl_add_u64 v[156:157], s[42:43], 0, v[0:1]
	s_mov_b32 m0, s70
	s_nop 0
	global_load_lds_dwordx4 v[156:157], off
	v_lshl_add_u64 v[156:157], s[42:43], 0, v[134:135]
	s_add_i32 m0, s70, 0x2000
	s_nop 0
	global_load_lds_dwordx4 v[156:157], off
	s_waitcnt vmcnt(6)
	s_barrier
	v_mfma_f32_16x16x32_bf16 v[54:57], v[228:231], v[172:175], v[54:57]
	v_mfma_f32_16x16x32_bf16 v[50:53], v[236:239], v[172:175], v[50:53]
	v_mfma_f32_16x16x32_bf16 v[38:41], v[228:231], v[184:187], v[38:41]
	v_mfma_f32_16x16x32_bf16 v[34:37], v[236:239], v[184:187], v[34:37]
	v_mfma_f32_16x16x32_bf16 v[22:25], v[228:231], v[192:195], v[22:25]
	v_mfma_f32_16x16x32_bf16 v[18:21], v[236:239], v[192:195], v[18:21]
	v_mfma_f32_16x16x32_bf16 v[6:9], v[228:231], v[220:223], v[6:9]
	v_mfma_f32_16x16x32_bf16 v[2:5], v[236:239], v[220:223], v[2:5]
	v_mfma_f32_16x16x32_bf16 v[54:57], v[232:235], v[180:183], v[54:57]
	v_mfma_f32_16x16x32_bf16 v[50:53], v[240:243], v[180:183], v[50:53]
	v_mfma_f32_16x16x32_bf16 v[38:41], v[232:235], v[188:191], v[38:41]
	v_mfma_f32_16x16x32_bf16 v[34:37], v[240:243], v[188:191], v[34:37]
	v_mfma_f32_16x16x32_bf16 v[22:25], v[232:235], v[216:219], v[22:25]
	v_mfma_f32_16x16x32_bf16 v[18:21], v[240:243], v[216:219], v[18:21]
	v_mfma_f32_16x16x32_bf16 v[6:9], v[232:235], v[224:227], v[6:9]
	v_mfma_f32_16x16x32_bf16 v[2:5], v[240:243], v[224:227], v[2:5]
	s_add_i32 s70, 0, 0x18000
	v_add_u32_e32 v168, s70, v145
	s_barrier
	ds_read_b128 v[156:159], v168
	ds_read_b128 v[160:163], v168 offset:1024
	ds_read_b128 v[164:167], v168 offset:2048
	ds_read_b128 v[168:171], v168 offset:3072
	s_add_u32 s42, s44, 0x80000
	s_addc_u32 s43, s45, 0
	s_mov_b32 m0, s60
	v_lshl_add_u64 v[208:209], s[42:43], 0, v[130:131]
	ds_read_b128 v[172:175], v147 offset:32768
	ds_read_b128 v[180:183], v147 offset:33792
	ds_read_b128 v[184:187], v147 offset:34816
	ds_read_b128 v[188:191], v147 offset:35840
	ds_read_b128 v[192:195], v147 offset:36864
	ds_read_b128 v[216:219], v147 offset:37888
	ds_read_b128 v[220:223], v147 offset:38912
	ds_read_b128 v[224:227], v147 offset:39936
	global_load_lds_dwordx4 v[208:209], off
	v_lshl_add_u64 v[208:209], s[42:43], 0, v[132:133]
	s_mov_b32 m0, s61
	s_nop 0
	global_load_lds_dwordx4 v[208:209], off
	s_waitcnt lgkmcnt(8)
	s_barrier
	s_waitcnt lgkmcnt(0)
	s_waitcnt lgkmcnt(0)
	v_mfma_f32_16x16x32_bf16 v[126:129], v[156:159], v[172:175], v[126:129]
	v_mfma_f32_16x16x32_bf16 v[122:125], v[164:167], v[172:175], v[122:125]
	v_mfma_f32_16x16x32_bf16 v[110:113], v[156:159], v[184:187], v[110:113]
	v_mfma_f32_16x16x32_bf16 v[106:109], v[164:167], v[184:187], v[106:109]
	v_mfma_f32_16x16x32_bf16 v[94:97], v[156:159], v[192:195], v[94:97]
	v_mfma_f32_16x16x32_bf16 v[90:93], v[164:167], v[192:195], v[90:93]
	v_mfma_f32_16x16x32_bf16 v[78:81], v[156:159], v[220:223], v[78:81]
	v_mfma_f32_16x16x32_bf16 v[74:77], v[164:167], v[220:223], v[74:77]
	v_mfma_f32_16x16x32_bf16 v[126:129], v[160:163], v[180:183], v[126:129]
	v_mfma_f32_16x16x32_bf16 v[122:125], v[168:171], v[180:183], v[122:125]
	v_mfma_f32_16x16x32_bf16 v[110:113], v[160:163], v[188:191], v[110:113]
	v_mfma_f32_16x16x32_bf16 v[106:109], v[168:171], v[188:191], v[106:109]
	v_mfma_f32_16x16x32_bf16 v[94:97], v[160:163], v[216:219], v[94:97]
	v_mfma_f32_16x16x32_bf16 v[90:93], v[168:171], v[216:219], v[90:93]
	v_mfma_f32_16x16x32_bf16 v[78:81], v[160:163], v[224:227], v[78:81]
	v_mfma_f32_16x16x32_bf16 v[74:77], v[168:171], v[224:227], v[74:77]
	s_barrier
	s_add_i32 s42, 0, 0x1c000
	s_add_i32 s43, s70, s56
	v_add_u32_e32 v179, s42, v145
	v_lshl_add_u64 v[176:177], v[176:177], 0, s[78:79]
	s_mov_b32 m0, s43
	ds_read_b128 v[228:231], v179
	ds_read_b128 v[232:235], v179 offset:1024
	ds_read_b128 v[236:239], v179 offset:2048
	ds_read_b128 v[240:243], v179 offset:3072
	global_load_lds_dwordx4 v[176:177], off
	v_lshl_add_u64 v[176:177], v[196:197], 0, s[78:79]
	s_add_i32 m0, s43, 0x2000
	s_nop 0
	global_load_lds_dwordx4 v[176:177], off
	s_barrier
	s_waitcnt lgkmcnt(0)
	s_waitcnt lgkmcnt(0)
	v_mfma_f32_16x16x32_bf16 v[118:121], v[228:231], v[172:175], v[118:121]
	v_mfma_f32_16x16x32_bf16 v[114:117], v[236:239], v[172:175], v[114:117]
	v_mfma_f32_16x16x32_bf16 v[102:105], v[228:231], v[184:187], v[102:105]
	v_mfma_f32_16x16x32_bf16 v[98:101], v[236:239], v[184:187], v[98:101]
	v_mfma_f32_16x16x32_bf16 v[86:89], v[228:231], v[192:195], v[86:89]
	v_mfma_f32_16x16x32_bf16 v[82:85], v[236:239], v[192:195], v[82:85]
	v_mfma_f32_16x16x32_bf16 v[70:73], v[228:231], v[220:223], v[70:73]
	v_mfma_f32_16x16x32_bf16 v[66:69], v[236:239], v[220:223], v[66:69]
	v_mfma_f32_16x16x32_bf16 v[118:121], v[232:235], v[180:183], v[118:121]
	v_mfma_f32_16x16x32_bf16 v[114:117], v[240:243], v[180:183], v[114:117]
	v_mfma_f32_16x16x32_bf16 v[102:105], v[232:235], v[188:191], v[102:105]
	v_mfma_f32_16x16x32_bf16 v[98:101], v[240:243], v[188:191], v[98:101]
	v_mfma_f32_16x16x32_bf16 v[86:89], v[232:235], v[216:219], v[86:89]
	v_mfma_f32_16x16x32_bf16 v[82:85], v[240:243], v[216:219], v[82:85]
	v_mfma_f32_16x16x32_bf16 v[70:73], v[232:235], v[224:227], v[70:73]
	v_mfma_f32_16x16x32_bf16 v[66:69], v[240:243], v[224:227], v[66:69]
	s_mov_b32 m0, s62
	v_lshl_add_u64 v[176:177], v[200:201], 0, s[78:79]
	s_barrier
	ds_read_b128 v[172:175], v147 offset:49152
	ds_read_b128 v[180:183], v147 offset:50176
	ds_read_b128 v[184:187], v147 offset:51200
	ds_read_b128 v[188:191], v147 offset:52224
	ds_read_b128 v[192:195], v147 offset:53248
	ds_read_b128 v[216:219], v147 offset:54272
	ds_read_b128 v[220:223], v147 offset:55296
	ds_read_b128 v[224:227], v147 offset:56320
	global_load_lds_dwordx4 v[176:177], off
	v_lshl_add_u64 v[176:177], v[206:207], 0, s[78:79]
	s_mov_b32 m0, s63
	s_nop 0
	global_load_lds_dwordx4 v[176:177], off
	s_barrier
	s_waitcnt lgkmcnt(0)
	s_waitcnt lgkmcnt(0)
	v_mfma_f32_16x16x32_bf16 v[62:65], v[156:159], v[172:175], v[62:65]
	v_mfma_f32_16x16x32_bf16 v[58:61], v[164:167], v[172:175], v[58:61]
	v_mfma_f32_16x16x32_bf16 v[46:49], v[156:159], v[184:187], v[46:49]
	v_mfma_f32_16x16x32_bf16 v[42:45], v[164:167], v[184:187], v[42:45]
	v_mfma_f32_16x16x32_bf16 v[30:33], v[156:159], v[192:195], v[30:33]
	v_mfma_f32_16x16x32_bf16 v[26:29], v[164:167], v[192:195], v[26:29]
	v_mfma_f32_16x16x32_bf16 v[14:17], v[156:159], v[220:223], v[14:17]
	v_mfma_f32_16x16x32_bf16 v[10:13], v[164:167], v[220:223], v[10:13]
	v_mfma_f32_16x16x32_bf16 v[62:65], v[160:163], v[180:183], v[62:65]
	v_mfma_f32_16x16x32_bf16 v[58:61], v[168:171], v[180:183], v[58:61]
	v_mfma_f32_16x16x32_bf16 v[46:49], v[160:163], v[188:191], v[46:49]
	v_mfma_f32_16x16x32_bf16 v[42:45], v[168:171], v[188:191], v[42:45]
	v_mfma_f32_16x16x32_bf16 v[30:33], v[160:163], v[216:219], v[30:33]
	v_mfma_f32_16x16x32_bf16 v[26:29], v[168:171], v[216:219], v[26:29]
	v_mfma_f32_16x16x32_bf16 v[14:17], v[160:163], v[224:227], v[14:17]
	v_mfma_f32_16x16x32_bf16 v[10:13], v[168:171], v[224:227], v[10:13]
	s_barrier
	s_add_u32 s4, s4, 0x80080
	s_addc_u32 s5, s5, 0
	s_add_i32 s42, s42, s56
	v_lshl_add_u64 v[156:157], s[4:5], 0, v[0:1]
	s_mov_b32 m0, s42
	s_nop 0
	global_load_lds_dwordx4 v[156:157], off
	v_lshl_add_u64 v[156:157], s[4:5], 0, v[134:135]
	s_add_i32 m0, s42, 0x2000
	s_nop 0
	global_load_lds_dwordx4 v[156:157], off
	s_waitcnt vmcnt(6)
	s_barrier
	v_mfma_f32_16x16x32_bf16 v[54:57], v[228:231], v[172:175], v[54:57]
	v_mfma_f32_16x16x32_bf16 v[50:53], v[236:239], v[172:175], v[50:53]
	v_mfma_f32_16x16x32_bf16 v[38:41], v[228:231], v[184:187], v[38:41]
	v_mfma_f32_16x16x32_bf16 v[34:37], v[236:239], v[184:187], v[34:37]
	v_mfma_f32_16x16x32_bf16 v[22:25], v[228:231], v[192:195], v[22:25]
	v_mfma_f32_16x16x32_bf16 v[18:21], v[236:239], v[192:195], v[18:21]
	v_mfma_f32_16x16x32_bf16 v[6:9], v[228:231], v[220:223], v[6:9]
	v_mfma_f32_16x16x32_bf16 v[2:5], v[236:239], v[220:223], v[2:5]
	v_mfma_f32_16x16x32_bf16 v[54:57], v[232:235], v[180:183], v[54:57]
	v_mfma_f32_16x16x32_bf16 v[50:53], v[240:243], v[180:183], v[50:53]
	v_mfma_f32_16x16x32_bf16 v[38:41], v[232:235], v[188:191], v[38:41]
	v_mfma_f32_16x16x32_bf16 v[34:37], v[240:243], v[188:191], v[34:37]
	v_mfma_f32_16x16x32_bf16 v[22:25], v[232:235], v[216:219], v[22:25]
	v_mfma_f32_16x16x32_bf16 v[18:21], v[240:243], v[216:219], v[18:21]
	v_mfma_f32_16x16x32_bf16 v[6:9], v[232:235], v[224:227], v[6:9]
	v_mfma_f32_16x16x32_bf16 v[2:5], v[240:243], v[224:227], v[2:5]
	s_add_i32 s69, s69, 2
	s_add_u32 s40, s40, 0x100
	s_addc_u32 s41, s41, 0
	s_add_u32 s67, s67, 0x100
	s_addc_u32 s68, s68, 0
	s_cmp_gt_u32 s69, 29
	s_barrier
	s_cbranch_scc1 .LBB0_200

.LBB0_847:
	s_add_u32 s24, s20, 0xfffe0080
	s_addc_u32 s25, s21, -1
	s_add_i32 s53, 0, 0x10000
	v_add_u32_e32 v140, s53, v143
	ds_read_b128 v[146:149], v140
	ds_read_b128 v[150:153], v140 offset:1024
	ds_read_b128 v[154:157], v140 offset:2048
	ds_read_b128 v[158:161], v140 offset:3072
	s_cmp_eq_u32 s52, 4
	s_cselect_b32 s27, s11, s25
	s_cselect_b32 s26, s48, s24
	s_cselect_b32 s25, s9, s51
	s_cselect_b32 s24, s49, s50
	v_lshl_add_u64 v[140:141], s[20:21], 0, v[136:137]
	s_add_i32 m0, s15, 0xc000
	ds_read_b128 v[162:165], v145
	ds_read_b128 v[166:169], v145 offset:1024
	ds_read_b128 v[170:173], v145 offset:2048
	ds_read_b128 v[174:177], v145 offset:3072
	ds_read_b128 v[180:183], v145 offset:4096
	ds_read_b128 v[184:187], v145 offset:5120
	ds_read_b128 v[188:191], v145 offset:6144
	ds_read_b128 v[192:195], v145 offset:7168
	global_load_lds_dwordx4 v[140:141], off
	v_lshl_add_u64 v[140:141], s[20:21], 0, v[138:139]
	s_add_i32 m0, s15, 0xe000
	s_nop 0
	global_load_lds_dwordx4 v[140:141], off
	s_waitcnt lgkmcnt(8)
	s_barrier
	s_waitcnt lgkmcnt(0)
	s_waitcnt lgkmcnt(0)
	v_mfma_f32_16x16x32_bf16 v[126:129], v[146:149], v[162:165], v[126:129]
	v_mfma_f32_16x16x32_bf16 v[122:125], v[154:157], v[162:165], v[122:125]
	v_mfma_f32_16x16x32_bf16 v[118:121], v[146:149], v[170:173], v[118:121]
	v_mfma_f32_16x16x32_bf16 v[110:113], v[154:157], v[170:173], v[110:113]
	v_mfma_f32_16x16x32_bf16 v[102:105], v[146:149], v[180:183], v[102:105]
	v_mfma_f32_16x16x32_bf16 v[94:97], v[154:157], v[180:183], v[94:97]
	v_mfma_f32_16x16x32_bf16 v[86:89], v[146:149], v[188:191], v[86:89]
	v_mfma_f32_16x16x32_bf16 v[78:81], v[154:157], v[188:191], v[78:81]
	v_mfma_f32_16x16x32_bf16 v[126:129], v[150:153], v[166:169], v[126:129]
	v_mfma_f32_16x16x32_bf16 v[122:125], v[158:161], v[166:169], v[122:125]
	v_mfma_f32_16x16x32_bf16 v[118:121], v[150:153], v[174:177], v[118:121]
	v_mfma_f32_16x16x32_bf16 v[110:113], v[158:161], v[174:177], v[110:113]
	v_mfma_f32_16x16x32_bf16 v[102:105], v[150:153], v[184:187], v[102:105]
	v_mfma_f32_16x16x32_bf16 v[94:97], v[158:161], v[184:187], v[94:97]
	v_mfma_f32_16x16x32_bf16 v[86:89], v[150:153], v[192:195], v[86:89]
	v_mfma_f32_16x16x32_bf16 v[78:81], v[158:161], v[192:195], v[78:81]
	s_barrier
	s_add_i32 s56, 0, 0x14000
	v_add_u32_e32 v140, s56, v143
	s_add_i32 s53, s53, s36
	ds_read_b128 v[216:219], v140
	ds_read_b128 v[220:223], v140 offset:1024
	ds_read_b128 v[224:227], v140 offset:2048
	ds_read_b128 v[228:231], v140 offset:3072
	v_lshl_add_u64 v[140:141], s[24:25], 0, v[0:1]
	s_mov_b32 m0, s53
	v_lshl_add_u64 v[196:197], s[24:25], 0, v[130:131]
	global_load_lds_dwordx4 v[140:141], off
	s_add_i32 m0, s53, 0x2000
	s_nop 0
	global_load_lds_dwordx4 v[196:197], off
	s_barrier
	s_waitcnt lgkmcnt(0)
	s_waitcnt lgkmcnt(0)
	v_mfma_f32_16x16x32_bf16 v[114:117], v[216:219], v[162:165], v[114:117]
	v_mfma_f32_16x16x32_bf16 v[106:109], v[224:227], v[162:165], v[106:109]
	v_mfma_f32_16x16x32_bf16 v[98:101], v[216:219], v[170:173], v[98:101]
	v_mfma_f32_16x16x32_bf16 v[90:93], v[224:227], v[170:173], v[90:93]
	v_mfma_f32_16x16x32_bf16 v[82:85], v[216:219], v[180:183], v[82:85]
	v_mfma_f32_16x16x32_bf16 v[74:77], v[224:227], v[180:183], v[74:77]
	v_mfma_f32_16x16x32_bf16 v[70:73], v[216:219], v[188:191], v[70:73]
	v_mfma_f32_16x16x32_bf16 v[66:69], v[224:227], v[188:191], v[66:69]
	v_mfma_f32_16x16x32_bf16 v[114:117], v[220:223], v[166:169], v[114:117]
	v_mfma_f32_16x16x32_bf16 v[106:109], v[228:231], v[166:169], v[106:109]
	v_mfma_f32_16x16x32_bf16 v[98:101], v[220:223], v[174:177], v[98:101]
	v_mfma_f32_16x16x32_bf16 v[90:93], v[228:231], v[174:177], v[90:93]
	v_mfma_f32_16x16x32_bf16 v[82:85], v[220:223], v[184:187], v[82:85]
	v_mfma_f32_16x16x32_bf16 v[74:77], v[228:231], v[184:187], v[74:77]
	v_mfma_f32_16x16x32_bf16 v[70:73], v[220:223], v[192:195], v[70:73]
	v_mfma_f32_16x16x32_bf16 v[66:69], v[228:231], v[192:195], v[66:69]
	s_mov_b32 m0, s15
	v_lshl_add_u64 v[200:201], s[26:27], 0, v[134:135]
	s_barrier
	ds_read_b128 v[162:165], v145 offset:16384
	ds_read_b128 v[166:169], v145 offset:17408
	ds_read_b128 v[170:173], v145 offset:18432
	ds_read_b128 v[174:177], v145 offset:19456
	ds_read_b128 v[180:183], v145 offset:20480
	ds_read_b128 v[184:187], v145 offset:21504
	ds_read_b128 v[188:191], v145 offset:22528
	ds_read_b128 v[192:195], v145 offset:23552
	global_load_lds_dwordx4 v[200:201], off
	v_lshl_add_u64 v[206:207], s[26:27], 0, v[132:133]
	s_mov_b32 m0, s40
	s_nop 0
	global_load_lds_dwordx4 v[206:207], off
	s_barrier
	s_waitcnt lgkmcnt(0)
	s_waitcnt lgkmcnt(0)
	v_mfma_f32_16x16x32_bf16 v[62:65], v[146:149], v[162:165], v[62:65]
	v_mfma_f32_16x16x32_bf16 v[58:61], v[154:157], v[162:165], v[58:61]
	v_mfma_f32_16x16x32_bf16 v[54:57], v[146:149], v[170:173], v[54:57]
	v_mfma_f32_16x16x32_bf16 v[46:49], v[154:157], v[170:173], v[46:49]
	v_mfma_f32_16x16x32_bf16 v[38:41], v[146:149], v[180:183], v[38:41]
	v_mfma_f32_16x16x32_bf16 v[30:33], v[154:157], v[180:183], v[30:33]
	v_mfma_f32_16x16x32_bf16 v[22:25], v[146:149], v[188:191], v[22:25]
	v_mfma_f32_16x16x32_bf16 v[14:17], v[154:157], v[188:191], v[14:17]
	v_mfma_f32_16x16x32_bf16 v[62:65], v[150:153], v[166:169], v[62:65]
	v_mfma_f32_16x16x32_bf16 v[58:61], v[158:161], v[166:169], v[58:61]
	v_mfma_f32_16x16x32_bf16 v[54:57], v[150:153], v[174:177], v[54:57]
	v_mfma_f32_16x16x32_bf16 v[46:49], v[158:161], v[174:177], v[46:49]
	v_mfma_f32_16x16x32_bf16 v[38:41], v[150:153], v[184:187], v[38:41]
	v_mfma_f32_16x16x32_bf16 v[30:33], v[158:161], v[184:187], v[30:33]
	v_mfma_f32_16x16x32_bf16 v[22:25], v[150:153], v[192:195], v[22:25]
	v_mfma_f32_16x16x32_bf16 v[14:17], v[158:161], v[192:195], v[14:17]
	s_barrier
	s_add_u32 s54, s24, 0x20000
	s_addc_u32 s55, s25, 0
	s_add_i32 s53, s56, s36
	v_lshl_add_u64 v[146:147], s[54:55], 0, v[0:1]
	s_mov_b32 m0, s53
	s_nop 0
	global_load_lds_dwordx4 v[146:147], off
	v_lshl_add_u64 v[146:147], s[54:55], 0, v[130:131]
	s_add_i32 m0, s53, 0x2000
	s_nop 0
	global_load_lds_dwordx4 v[146:147], off
	s_waitcnt vmcnt(6)
	s_barrier
	v_mfma_f32_16x16x32_bf16 v[50:53], v[216:219], v[162:165], v[50:53]
	v_mfma_f32_16x16x32_bf16 v[42:45], v[224:227], v[162:165], v[42:45]
	v_mfma_f32_16x16x32_bf16 v[34:37], v[216:219], v[170:173], v[34:37]
	v_mfma_f32_16x16x32_bf16 v[26:29], v[224:227], v[170:173], v[26:29]
	v_mfma_f32_16x16x32_bf16 v[18:21], v[216:219], v[180:183], v[18:21]
	v_mfma_f32_16x16x32_bf16 v[10:13], v[224:227], v[180:183], v[10:13]
	v_mfma_f32_16x16x32_bf16 v[6:9], v[216:219], v[188:191], v[6:9]
	v_mfma_f32_16x16x32_bf16 v[2:5], v[224:227], v[188:191], v[2:5]
	v_mfma_f32_16x16x32_bf16 v[50:53], v[220:223], v[166:169], v[50:53]
	v_mfma_f32_16x16x32_bf16 v[42:45], v[228:231], v[166:169], v[42:45]
	v_mfma_f32_16x16x32_bf16 v[34:37], v[220:223], v[174:177], v[34:37]
	v_mfma_f32_16x16x32_bf16 v[26:29], v[228:231], v[174:177], v[26:29]
	v_mfma_f32_16x16x32_bf16 v[18:21], v[220:223], v[184:187], v[18:21]
	v_mfma_f32_16x16x32_bf16 v[10:13], v[228:231], v[184:187], v[10:13]
	v_mfma_f32_16x16x32_bf16 v[6:9], v[220:223], v[192:195], v[6:9]
	v_mfma_f32_16x16x32_bf16 v[2:5], v[228:231], v[192:195], v[2:5]
	s_add_i32 s53, 0, 0x18000
	v_add_u32_e32 v158, s53, v143
	s_barrier
	ds_read_b128 v[146:149], v158
	ds_read_b128 v[150:153], v158 offset:1024
	ds_read_b128 v[154:157], v158 offset:2048
	ds_read_b128 v[158:161], v158 offset:3072
	s_add_u32 s26, s26, 0x20000
	s_addc_u32 s27, s27, 0
	s_mov_b32 m0, s41
	v_lshl_add_u64 v[208:209], s[26:27], 0, v[134:135]
	ds_read_b128 v[162:165], v145 offset:32768
	ds_read_b128 v[166:169], v145 offset:33792
	ds_read_b128 v[170:173], v145 offset:34816
	ds_read_b128 v[174:177], v145 offset:35840
	ds_read_b128 v[180:183], v145 offset:36864
	ds_read_b128 v[184:187], v145 offset:37888
	ds_read_b128 v[188:191], v145 offset:38912
	ds_read_b128 v[192:195], v145 offset:39936
	global_load_lds_dwordx4 v[208:209], off
	v_lshl_add_u64 v[208:209], s[26:27], 0, v[132:133]
	s_mov_b32 m0, s42
	s_nop 0
	global_load_lds_dwordx4 v[208:209], off
	s_waitcnt lgkmcnt(8)
	s_barrier
	s_waitcnt lgkmcnt(0)
	s_waitcnt lgkmcnt(0)
	v_mfma_f32_16x16x32_bf16 v[126:129], v[146:149], v[162:165], v[126:129]
	v_mfma_f32_16x16x32_bf16 v[122:125], v[154:157], v[162:165], v[122:125]
	v_mfma_f32_16x16x32_bf16 v[118:121], v[146:149], v[170:173], v[118:121]
	v_mfma_f32_16x16x32_bf16 v[110:113], v[154:157], v[170:173], v[110:113]
	v_mfma_f32_16x16x32_bf16 v[102:105], v[146:149], v[180:183], v[102:105]
	v_mfma_f32_16x16x32_bf16 v[94:97], v[154:157], v[180:183], v[94:97]
	v_mfma_f32_16x16x32_bf16 v[86:89], v[146:149], v[188:191], v[86:89]
	v_mfma_f32_16x16x32_bf16 v[78:81], v[154:157], v[188:191], v[78:81]
	v_mfma_f32_16x16x32_bf16 v[126:129], v[150:153], v[166:169], v[126:129]
	v_mfma_f32_16x16x32_bf16 v[122:125], v[158:161], v[166:169], v[122:125]
	v_mfma_f32_16x16x32_bf16 v[118:121], v[150:153], v[174:177], v[118:121]
	v_mfma_f32_16x16x32_bf16 v[110:113], v[158:161], v[174:177], v[110:113]
	v_mfma_f32_16x16x32_bf16 v[102:105], v[150:153], v[184:187], v[102:105]
	v_mfma_f32_16x16x32_bf16 v[94:97], v[158:161], v[184:187], v[94:97]
	v_mfma_f32_16x16x32_bf16 v[86:89], v[150:153], v[192:195], v[86:89]
	v_mfma_f32_16x16x32_bf16 v[78:81], v[158:161], v[192:195], v[78:81]
	s_barrier
	s_add_i32 s26, 0, 0x1c000
	s_add_i32 s27, s53, s36
	v_add_u32_e32 v179, s26, v143
	v_lshl_add_u64 v[140:141], v[140:141], 0, s[78:79]
	s_mov_b32 m0, s27
	ds_read_b128 v[216:219], v179
	ds_read_b128 v[220:223], v179 offset:1024
	ds_read_b128 v[224:227], v179 offset:2048
	ds_read_b128 v[228:231], v179 offset:3072
	global_load_lds_dwordx4 v[140:141], off
	v_lshl_add_u64 v[140:141], v[196:197], 0, s[78:79]
	s_add_i32 m0, s27, 0x2000
	s_nop 0
	global_load_lds_dwordx4 v[140:141], off
	s_barrier
	s_waitcnt lgkmcnt(0)
	s_waitcnt lgkmcnt(0)
	v_mfma_f32_16x16x32_bf16 v[114:117], v[216:219], v[162:165], v[114:117]
	v_mfma_f32_16x16x32_bf16 v[106:109], v[224:227], v[162:165], v[106:109]
	v_mfma_f32_16x16x32_bf16 v[98:101], v[216:219], v[170:173], v[98:101]
	v_mfma_f32_16x16x32_bf16 v[90:93], v[224:227], v[170:173], v[90:93]
	v_mfma_f32_16x16x32_bf16 v[82:85], v[216:219], v[180:183], v[82:85]
	v_mfma_f32_16x16x32_bf16 v[74:77], v[224:227], v[180:183], v[74:77]
	v_mfma_f32_16x16x32_bf16 v[70:73], v[216:219], v[188:191], v[70:73]
	v_mfma_f32_16x16x32_bf16 v[66:69], v[224:227], v[188:191], v[66:69]
	v_mfma_f32_16x16x32_bf16 v[114:117], v[220:223], v[166:169], v[114:117]
	v_mfma_f32_16x16x32_bf16 v[106:109], v[228:231], v[166:169], v[106:109]
	v_mfma_f32_16x16x32_bf16 v[98:101], v[220:223], v[174:177], v[98:101]
	v_mfma_f32_16x16x32_bf16 v[90:93], v[228:231], v[174:177], v[90:93]
	v_mfma_f32_16x16x32_bf16 v[82:85], v[220:223], v[184:187], v[82:85]
	v_mfma_f32_16x16x32_bf16 v[74:77], v[228:231], v[184:187], v[74:77]
	v_mfma_f32_16x16x32_bf16 v[70:73], v[220:223], v[192:195], v[70:73]
	v_mfma_f32_16x16x32_bf16 v[66:69], v[228:231], v[192:195], v[66:69]
	s_mov_b32 m0, s45
	v_lshl_add_u64 v[140:141], v[200:201], 0, s[78:79]
	s_barrier
	ds_read_b128 v[162:165], v145 offset:49152
	ds_read_b128 v[166:169], v145 offset:50176
	ds_read_b128 v[170:173], v145 offset:51200
	ds_read_b128 v[174:177], v145 offset:52224
	ds_read_b128 v[180:183], v145 offset:53248
	ds_read_b128 v[184:187], v145 offset:54272
	ds_read_b128 v[188:191], v145 offset:55296
	ds_read_b128 v[192:195], v145 offset:56320
	global_load_lds_dwordx4 v[140:141], off
	v_lshl_add_u64 v[140:141], v[206:207], 0, s[78:79]
	s_mov_b32 m0, s46
	s_nop 0
	global_load_lds_dwordx4 v[140:141], off
	s_barrier
	s_waitcnt lgkmcnt(0)
	s_waitcnt lgkmcnt(0)
	v_mfma_f32_16x16x32_bf16 v[62:65], v[146:149], v[162:165], v[62:65]
	v_mfma_f32_16x16x32_bf16 v[58:61], v[154:157], v[162:165], v[58:61]
	v_mfma_f32_16x16x32_bf16 v[54:57], v[146:149], v[170:173], v[54:57]
	v_mfma_f32_16x16x32_bf16 v[46:49], v[154:157], v[170:173], v[46:49]
	v_mfma_f32_16x16x32_bf16 v[38:41], v[146:149], v[180:183], v[38:41]
	v_mfma_f32_16x16x32_bf16 v[30:33], v[154:157], v[180:183], v[30:33]
	v_mfma_f32_16x16x32_bf16 v[22:25], v[146:149], v[188:191], v[22:25]
	v_mfma_f32_16x16x32_bf16 v[14:17], v[154:157], v[188:191], v[14:17]
	v_mfma_f32_16x16x32_bf16 v[62:65], v[150:153], v[166:169], v[62:65]
	v_mfma_f32_16x16x32_bf16 v[58:61], v[158:161], v[166:169], v[58:61]
	v_mfma_f32_16x16x32_bf16 v[54:57], v[150:153], v[174:177], v[54:57]
	v_mfma_f32_16x16x32_bf16 v[46:49], v[158:161], v[174:177], v[46:49]
	v_mfma_f32_16x16x32_bf16 v[38:41], v[150:153], v[184:187], v[38:41]
	v_mfma_f32_16x16x32_bf16 v[30:33], v[158:161], v[184:187], v[30:33]
	v_mfma_f32_16x16x32_bf16 v[22:25], v[150:153], v[192:195], v[22:25]
	v_mfma_f32_16x16x32_bf16 v[14:17], v[158:161], v[192:195], v[14:17]
	s_barrier
	s_add_u32 s24, s24, 0x20080
	s_addc_u32 s25, s25, 0
	s_add_i32 s26, s26, s36
	v_lshl_add_u64 v[140:141], s[24:25], 0, v[0:1]
	s_mov_b32 m0, s26
	s_nop 0
	global_load_lds_dwordx4 v[140:141], off
	v_lshl_add_u64 v[140:141], s[24:25], 0, v[130:131]
	s_add_i32 m0, s26, 0x2000
	s_nop 0
	global_load_lds_dwordx4 v[140:141], off
	s_waitcnt vmcnt(6)
	s_barrier
	v_mfma_f32_16x16x32_bf16 v[50:53], v[216:219], v[162:165], v[50:53]
	v_mfma_f32_16x16x32_bf16 v[42:45], v[224:227], v[162:165], v[42:45]
	v_mfma_f32_16x16x32_bf16 v[34:37], v[216:219], v[170:173], v[34:37]
	v_mfma_f32_16x16x32_bf16 v[26:29], v[224:227], v[170:173], v[26:29]
	v_mfma_f32_16x16x32_bf16 v[18:21], v[216:219], v[180:183], v[18:21]
	v_mfma_f32_16x16x32_bf16 v[10:13], v[224:227], v[180:183], v[10:13]
	v_mfma_f32_16x16x32_bf16 v[6:9], v[216:219], v[188:191], v[6:9]
	v_mfma_f32_16x16x32_bf16 v[2:5], v[224:227], v[188:191], v[2:5]
	v_mfma_f32_16x16x32_bf16 v[50:53], v[220:223], v[166:169], v[50:53]
	v_mfma_f32_16x16x32_bf16 v[42:45], v[228:231], v[166:169], v[42:45]
	v_mfma_f32_16x16x32_bf16 v[34:37], v[220:223], v[174:177], v[34:37]
	v_mfma_f32_16x16x32_bf16 v[26:29], v[228:231], v[174:177], v[26:29]
	v_mfma_f32_16x16x32_bf16 v[18:21], v[220:223], v[184:187], v[18:21]
	v_mfma_f32_16x16x32_bf16 v[10:13], v[228:231], v[184:187], v[10:13]
	v_mfma_f32_16x16x32_bf16 v[6:9], v[220:223], v[192:195], v[6:9]
	v_mfma_f32_16x16x32_bf16 v[2:5], v[228:231], v[192:195], v[2:5]
	s_add_i32 s52, s52, 2
	s_add_u32 s20, s20, 0x100
	s_addc_u32 s21, s21, 0
	s_add_u32 s50, s50, 0x100
	s_addc_u32 s51, s51, 0
	s_cmp_gt_u32 s52, 5
	s_barrier
	s_cbranch_scc0 .LBB0_847
	v_lshl_add_u32 v148, s14, 8, v142
	v_lshl_or_b32 v140, s47, 8, v144
	v_ashrrev_i32_e32 v141, 31, v140
	v_mad_i64_i32 v[146:147], s[20:21], s44, v148, 0
	v_lshl_add_u64 v[146:147], v[146:147], 1, s[6:7]
	v_lshlrev_b64 v[140:141], 1, v[140:141]
	v_lshl_add_u64 v[146:147], v[146:147], 0, v[140:141]
	v_cvt_pk_bf16_f32 v126, v126, v127
	v_cvt_pk_bf16_f32 v127, v128, v129
	v_cvt_pk_bf16_f32 v128, v122, v123
	v_cvt_pk_bf16_f32 v129, v124, v125
	global_store_dwordx4 v[146:147], v[126:129], off
	v_cvt_pk_bf16_f32 v114, v114, v115
	v_cvt_pk_bf16_f32 v115, v116, v117
	v_cvt_pk_bf16_f32 v116, v106, v107
	v_or_b32_e32 v106, 16, v148
	v_mad_i64_i32 v[106:107], s[20:21], s44, v106, 0
	v_lshl_add_u64 v[106:107], v[106:107], 1, s[6:7]
	v_cvt_pk_bf16_f32 v117, v108, v109
	global_store_dwordx4 v[146:147], v[114:117], off offset:256
	s_and_b64 vcc, exec, s[0:1]
	s_mov_b32 s47, s8
	v_lshl_add_u64 v[114:115], v[106:107], 0, v[140:141]
	v_cvt_pk_bf16_f32 v106, v118, v119
	v_cvt_pk_bf16_f32 v107, v120, v121
	v_cvt_pk_bf16_f32 v108, v110, v111
	v_cvt_pk_bf16_f32 v109, v112, v113
	global_store_dwordx4 v[114:115], v[106:109], off
	v_cvt_pk_bf16_f32 v98, v98, v99
	v_cvt_pk_bf16_f32 v99, v100, v101
	v_cvt_pk_bf16_f32 v100, v90, v91
	v_or_b32_e32 v90, 32, v148
	v_mad_i64_i32 v[90:91], s[20:21], s44, v90, 0
	v_lshl_add_u64 v[90:91], v[90:91], 1, s[6:7]
	v_cvt_pk_bf16_f32 v101, v92, v93
	global_store_dwordx4 v[114:115], v[98:101], off offset:256
	s_mov_b32 s14, s10
	s_mov_b64 s[24:25], s[18:19]
	v_lshl_add_u64 v[98:99], v[90:91], 0, v[140:141]
	v_cvt_pk_bf16_f32 v90, v102, v103
	v_cvt_pk_bf16_f32 v91, v104, v105
	v_cvt_pk_bf16_f32 v92, v94, v95
	v_cvt_pk_bf16_f32 v93, v96, v97
	global_store_dwordx4 v[98:99], v[90:93], off
	v_cvt_pk_bf16_f32 v82, v82, v83
	v_cvt_pk_bf16_f32 v83, v84, v85
	v_cvt_pk_bf16_f32 v84, v74, v75
	v_or_b32_e32 v74, 48, v148
	v_mad_i64_i32 v[74:75], s[20:21], s44, v74, 0
	v_lshl_add_u64 v[74:75], v[74:75], 1, s[6:7]
	v_cvt_pk_bf16_f32 v85, v76, v77
	global_store_dwordx4 v[98:99], v[82:85], off offset:256
	s_nop 1
	v_lshl_add_u64 v[82:83], v[74:75], 0, v[140:141]
	v_cvt_pk_bf16_f32 v74, v86, v87
	v_cvt_pk_bf16_f32 v75, v88, v89
	v_cvt_pk_bf16_f32 v76, v78, v79
	v_cvt_pk_bf16_f32 v77, v80, v81
	global_store_dwordx4 v[82:83], v[74:77], off
	v_cvt_pk_bf16_f32 v70, v70, v71
	v_cvt_pk_bf16_f32 v71, v72, v73
	v_cvt_pk_bf16_f32 v72, v66, v67
	v_add_u32_e32 v66, 0x80, v148
	v_mad_i64_i32 v[66:67], s[20:21], s44, v66, 0
	v_lshl_add_u64 v[66:67], v[66:67], 1, s[6:7]
	v_lshl_add_u64 v[66:67], v[66:67], 0, v[140:141]
	v_cvt_pk_bf16_f32 v73, v68, v69
	global_store_dwordx4 v[82:83], v[70:73], off offset:256
	v_cvt_pk_bf16_f32 v62, v62, v63
	v_cvt_pk_bf16_f32 v63, v64, v65
	v_cvt_pk_bf16_f32 v64, v58, v59
	v_cvt_pk_bf16_f32 v65, v60, v61
	global_store_dwordx4 v[66:67], v[62:65], off
	v_cvt_pk_bf16_f32 v50, v50, v51
	v_cvt_pk_bf16_f32 v51, v52, v53
	v_cvt_pk_bf16_f32 v52, v42, v43
	v_add_u32_e32 v42, 0x90, v148
	v_mad_i64_i32 v[42:43], s[20:21], s44, v42, 0
	v_lshl_add_u64 v[42:43], v[42:43], 1, s[6:7]
	v_cvt_pk_bf16_f32 v53, v44, v45
	global_store_dwordx4 v[66:67], v[50:53], off offset:256
	s_nop 1
	v_lshl_add_u64 v[50:51], v[42:43], 0, v[140:141]
	v_cvt_pk_bf16_f32 v42, v54, v55
	v_cvt_pk_bf16_f32 v43, v56, v57
	v_cvt_pk_bf16_f32 v44, v46, v47
	v_cvt_pk_bf16_f32 v45, v48, v49
	global_store_dwordx4 v[50:51], v[42:45], off
	v_cvt_pk_bf16_f32 v34, v34, v35
	v_cvt_pk_bf16_f32 v35, v36, v37
	v_cvt_pk_bf16_f32 v36, v26, v27
	v_add_u32_e32 v26, 0xa0, v148
	v_mad_i64_i32 v[26:27], s[20:21], s44, v26, 0
	v_lshl_add_u64 v[26:27], v[26:27], 1, s[6:7]
	v_cvt_pk_bf16_f32 v37, v28, v29
	global_store_dwordx4 v[50:51], v[34:37], off offset:256
	s_nop 1
	v_lshl_add_u64 v[34:35], v[26:27], 0, v[140:141]
	v_cvt_pk_bf16_f32 v26, v38, v39
	v_cvt_pk_bf16_f32 v27, v40, v41
	v_cvt_pk_bf16_f32 v28, v30, v31
	v_cvt_pk_bf16_f32 v29, v32, v33
	global_store_dwordx4 v[34:35], v[26:29], off
	v_cvt_pk_bf16_f32 v18, v18, v19
	v_cvt_pk_bf16_f32 v19, v20, v21
	v_cvt_pk_bf16_f32 v20, v10, v11
	v_add_u32_e32 v10, 0xb0, v148
	v_mad_i64_i32 v[10:11], s[20:21], s44, v10, 0
	v_lshl_add_u64 v[10:11], v[10:11], 1, s[6:7]
	v_cvt_pk_bf16_f32 v21, v12, v13
	global_store_dwordx4 v[34:35], v[18:21], off offset:256
	s_mov_b64 s[20:21], s[16:17]
	s_nop 0
	v_lshl_add_u64 v[18:19], v[10:11], 0, v[140:141]
	v_cvt_pk_bf16_f32 v10, v22, v23
	v_cvt_pk_bf16_f32 v11, v24, v25
	v_cvt_pk_bf16_f32 v12, v14, v15
	v_cvt_pk_bf16_f32 v13, v16, v17
	global_store_dwordx4 v[18:19], v[10:13], off
	v_cvt_pk_bf16_f32 v6, v6, v7
	v_cvt_pk_bf16_f32 v7, v8, v9
	v_cvt_pk_bf16_f32 v8, v2, v3
	v_cvt_pk_bf16_f32 v9, v4, v5
	global_store_dwordx4 v[18:19], v[6:9], off offset:256
	s_cbranch_vccz .LBB0_844
	s_waitcnt vmcnt(0)
	s_cmpk_gt_u32 s28, 0xff
	s_cbranch_scc1 .LBB0_838
	s_barrier
	s_branch .LBB0_838

.LBB0_1348:
	s_add_i32 s40, s14, 2
	s_add_u32 s16, s12, 0x80
	s_addc_u32 s15, s13, 0
	s_add_i32 s41, 0, 0x10000
	v_add_u32_e32 v126, s41, v216
	ds_read_b128 v[114:117], v126
	ds_read_b128 v[118:121], v126 offset:1024
	ds_read_b128 v[122:125], v126 offset:2048
	ds_read_b128 v[126:129], v126 offset:3072
	s_cmp_eq_u32 s30, s14
	s_cselect_b32 s14, s4, s16
	s_cselect_b32 s15, s5, s15
	s_cselect_b32 s17, s7, s39
	s_cselect_b32 s16, s6, s38
	v_lshl_add_u64 v[186:187], s[12:13], 0, v[182:183]
	s_add_i32 m0, s23, 0xc000
	ds_read_b128 v[130:133], v218
	ds_read_b128 v[134:137], v218 offset:1024
	ds_read_b128 v[138:141], v218 offset:2048
	ds_read_b128 v[142:145], v218 offset:3072
	ds_read_b128 v[154:157], v218 offset:4096
	ds_read_b128 v[162:165], v218 offset:5120
	ds_read_b128 v[170:173], v218 offset:6144
	ds_read_b128 v[174:177], v218 offset:7168
	global_load_lds_dwordx4 v[186:187], off
	v_lshl_add_u64 v[186:187], s[12:13], 0, v[184:185]
	s_add_i32 m0, s23, 0xe000
	s_nop 0
	global_load_lds_dwordx4 v[186:187], off
	s_waitcnt lgkmcnt(8)
	s_barrier
	s_waitcnt lgkmcnt(0)
	s_waitcnt lgkmcnt(0)
	v_mfma_f32_16x16x32_bf16 v[166:169], v[114:117], v[130:133], v[166:169]
	v_mfma_f32_16x16x32_bf16 v[158:161], v[122:125], v[130:133], v[158:161]
	v_mfma_f32_16x16x32_bf16 v[110:113], v[114:117], v[138:141], v[110:113]
	v_mfma_f32_16x16x32_bf16 v[106:109], v[122:125], v[138:141], v[106:109]
	v_mfma_f32_16x16x32_bf16 v[94:97], v[114:117], v[154:157], v[94:97]
	v_mfma_f32_16x16x32_bf16 v[90:93], v[122:125], v[154:157], v[90:93]
	v_mfma_f32_16x16x32_bf16 v[78:81], v[114:117], v[170:173], v[78:81]
	v_mfma_f32_16x16x32_bf16 v[74:77], v[122:125], v[170:173], v[74:77]
	v_mfma_f32_16x16x32_bf16 v[166:169], v[118:121], v[134:137], v[166:169]
	v_mfma_f32_16x16x32_bf16 v[158:161], v[126:129], v[134:137], v[158:161]
	v_mfma_f32_16x16x32_bf16 v[110:113], v[118:121], v[142:145], v[110:113]
	v_mfma_f32_16x16x32_bf16 v[106:109], v[126:129], v[142:145], v[106:109]
	v_mfma_f32_16x16x32_bf16 v[94:97], v[118:121], v[162:165], v[94:97]
	v_mfma_f32_16x16x32_bf16 v[90:93], v[126:129], v[162:165], v[90:93]
	v_mfma_f32_16x16x32_bf16 v[78:81], v[118:121], v[174:177], v[78:81]
	v_mfma_f32_16x16x32_bf16 v[74:77], v[126:129], v[174:177], v[74:77]
	s_barrier
	s_add_i32 s42, 0, 0x14000
	s_add_i32 s41, s41, s22
	v_add_u32_e32 v199, s42, v216
	v_lshl_add_u64 v[200:201], s[16:17], 0, v[0:1]
	s_mov_b32 m0, s41
	ds_read_b128 v[186:189], v199
	ds_read_b128 v[190:193], v199 offset:1024
	ds_read_b128 v[194:197], v199 offset:2048
	ds_read_b128 v[206:209], v199 offset:3072
	global_load_lds_dwordx4 v[200:201], off
	v_lshl_add_u64 v[220:221], s[16:17], 0, v[180:181]
	s_add_i32 m0, s41, 0x2000
	s_nop 0
	global_load_lds_dwordx4 v[220:221], off
	s_barrier
	s_waitcnt lgkmcnt(0)
	s_waitcnt lgkmcnt(0)
	v_mfma_f32_16x16x32_bf16 v[150:153], v[186:189], v[130:133], v[150:153]
	v_mfma_f32_16x16x32_bf16 v[102:105], v[186:189], v[138:141], v[102:105]
	v_mfma_f32_16x16x32_bf16 v[98:101], v[194:197], v[138:141], v[98:101]
	v_mfma_f32_16x16x32_bf16 v[86:89], v[186:189], v[154:157], v[86:89]
	v_mfma_f32_16x16x32_bf16 v[82:85], v[194:197], v[154:157], v[82:85]
	v_mfma_f32_16x16x32_bf16 v[70:73], v[186:189], v[170:173], v[70:73]
	v_mfma_f32_16x16x32_bf16 v[66:69], v[194:197], v[170:173], v[66:69]
	v_mfma_f32_16x16x32_bf16 v[150:153], v[190:193], v[134:137], v[150:153]
	v_mfma_f32_16x16x32_bf16 v[130:133], v[194:197], v[130:133], v[146:149]
	v_mfma_f32_16x16x32_bf16 v[102:105], v[190:193], v[142:145], v[102:105]
	v_mfma_f32_16x16x32_bf16 v[98:101], v[206:209], v[142:145], v[98:101]
	v_mfma_f32_16x16x32_bf16 v[86:89], v[190:193], v[162:165], v[86:89]
	v_mfma_f32_16x16x32_bf16 v[82:85], v[206:209], v[162:165], v[82:85]
	v_mfma_f32_16x16x32_bf16 v[70:73], v[190:193], v[174:177], v[70:73]
	v_mfma_f32_16x16x32_bf16 v[66:69], v[206:209], v[174:177], v[66:69]
	v_mfma_f32_16x16x32_bf16 v[130:133], v[206:209], v[134:137], v[130:133]
	s_mov_b32 m0, s23
	v_lshl_add_u64 v[222:223], s[14:15], 0, v[0:1]
	s_barrier
	ds_read_b128 v[134:137], v218 offset:16384
	ds_read_b128 v[138:141], v218 offset:17408
	ds_read_b128 v[142:145], v218 offset:18432
	ds_read_b128 v[146:149], v218 offset:19456
	ds_read_b128 v[154:157], v218 offset:20480
	ds_read_b128 v[162:165], v218 offset:21504
	ds_read_b128 v[170:173], v218 offset:22528
	ds_read_b128 v[174:177], v218 offset:23552
	global_load_lds_dwordx4 v[222:223], off
	v_lshl_add_u64 v[224:225], s[14:15], 0, v[180:181]
	s_mov_b32 m0, s24
	s_nop 0
	global_load_lds_dwordx4 v[224:225], off
	s_barrier
	s_waitcnt lgkmcnt(0)
	s_waitcnt lgkmcnt(0)
	v_mfma_f32_16x16x32_bf16 v[62:65], v[114:117], v[134:137], v[62:65]
	v_mfma_f32_16x16x32_bf16 v[58:61], v[122:125], v[134:137], v[58:61]
	v_mfma_f32_16x16x32_bf16 v[46:49], v[114:117], v[142:145], v[46:49]
	v_mfma_f32_16x16x32_bf16 v[42:45], v[122:125], v[142:145], v[42:45]
	v_mfma_f32_16x16x32_bf16 v[30:33], v[114:117], v[154:157], v[30:33]
	v_mfma_f32_16x16x32_bf16 v[26:29], v[122:125], v[154:157], v[26:29]
	v_mfma_f32_16x16x32_bf16 v[14:17], v[114:117], v[170:173], v[14:17]
	v_mfma_f32_16x16x32_bf16 v[10:13], v[122:125], v[170:173], v[10:13]
	v_mfma_f32_16x16x32_bf16 v[62:65], v[118:121], v[138:141], v[62:65]
	v_mfma_f32_16x16x32_bf16 v[58:61], v[126:129], v[138:141], v[58:61]
	v_mfma_f32_16x16x32_bf16 v[46:49], v[118:121], v[146:149], v[46:49]
	v_mfma_f32_16x16x32_bf16 v[42:45], v[126:129], v[146:149], v[42:45]
	v_mfma_f32_16x16x32_bf16 v[30:33], v[118:121], v[162:165], v[30:33]
	v_mfma_f32_16x16x32_bf16 v[26:29], v[126:129], v[162:165], v[26:29]
	v_mfma_f32_16x16x32_bf16 v[14:17], v[118:121], v[174:177], v[14:17]
	v_mfma_f32_16x16x32_bf16 v[10:13], v[126:129], v[174:177], v[10:13]
	s_barrier
	s_add_u32 s16, s16, s2
	s_addc_u32 s17, s17, 0
	s_add_i32 s41, s42, s22
	v_lshl_add_u64 v[226:227], s[16:17], 0, v[0:1]
	s_mov_b32 m0, s41
	v_lshl_add_u64 v[228:229], s[16:17], 0, v[180:181]
	global_load_lds_dwordx4 v[226:227], off
	s_add_i32 m0, s41, 0x2000
	s_nop 0
	global_load_lds_dwordx4 v[228:229], off
	s_waitcnt vmcnt(6)
	s_barrier
	v_mfma_f32_16x16x32_bf16 v[54:57], v[186:189], v[134:137], v[54:57]
	v_mfma_f32_16x16x32_bf16 v[50:53], v[194:197], v[134:137], v[50:53]
	v_mfma_f32_16x16x32_bf16 v[38:41], v[186:189], v[142:145], v[38:41]
	v_mfma_f32_16x16x32_bf16 v[34:37], v[194:197], v[142:145], v[34:37]
	v_mfma_f32_16x16x32_bf16 v[22:25], v[186:189], v[154:157], v[22:25]
	v_mfma_f32_16x16x32_bf16 v[18:21], v[194:197], v[154:157], v[18:21]
	v_mfma_f32_16x16x32_bf16 v[6:9], v[186:189], v[170:173], v[6:9]
	v_mfma_f32_16x16x32_bf16 v[2:5], v[194:197], v[170:173], v[2:5]
	v_mfma_f32_16x16x32_bf16 v[54:57], v[190:193], v[138:141], v[54:57]
	v_mfma_f32_16x16x32_bf16 v[50:53], v[206:209], v[138:141], v[50:53]
	v_mfma_f32_16x16x32_bf16 v[38:41], v[190:193], v[146:149], v[38:41]
	v_mfma_f32_16x16x32_bf16 v[34:37], v[206:209], v[146:149], v[34:37]
	v_mfma_f32_16x16x32_bf16 v[22:25], v[190:193], v[162:165], v[22:25]
	v_mfma_f32_16x16x32_bf16 v[18:21], v[206:209], v[162:165], v[18:21]
	v_mfma_f32_16x16x32_bf16 v[6:9], v[190:193], v[174:177], v[6:9]
	v_mfma_f32_16x16x32_bf16 v[2:5], v[206:209], v[174:177], v[2:5]
	s_add_i32 s16, 0, 0x18000
	v_add_u32_e32 v126, s16, v216
	s_barrier
	ds_read_b128 v[114:117], v126
	ds_read_b128 v[118:121], v126 offset:1024
	ds_read_b128 v[122:125], v126 offset:2048
	ds_read_b128 v[126:129], v126 offset:3072
	s_add_u32 s14, s14, s2
	s_addc_u32 s15, s15, 0
	s_mov_b32 m0, s25
	v_lshl_add_u64 v[146:147], s[14:15], 0, v[0:1]
	ds_read_b128 v[134:137], v218 offset:32768
	ds_read_b128 v[138:141], v218 offset:33792
	ds_read_b128 v[142:145], v218 offset:34816
	ds_read_b128 v[154:157], v218 offset:35840
	ds_read_b128 v[162:165], v218 offset:36864
	ds_read_b128 v[170:173], v218 offset:37888
	ds_read_b128 v[174:177], v218 offset:38912
	ds_read_b128 v[186:189], v218 offset:39936
	global_load_lds_dwordx4 v[146:147], off
	v_lshl_add_u64 v[146:147], s[14:15], 0, v[180:181]
	s_mov_b32 m0, s26
	s_nop 0
	global_load_lds_dwordx4 v[146:147], off
	s_waitcnt lgkmcnt(8)
	s_barrier
	s_waitcnt lgkmcnt(0)
	s_waitcnt lgkmcnt(0)
	v_mfma_f32_16x16x32_bf16 v[146:149], v[114:117], v[134:137], v[166:169]
	v_mfma_f32_16x16x32_bf16 v[166:169], v[118:121], v[138:141], v[146:149]
	v_mfma_f32_16x16x32_bf16 v[146:149], v[122:125], v[134:137], v[158:161]
	v_mfma_f32_16x16x32_bf16 v[110:113], v[114:117], v[142:145], v[110:113]
	v_mfma_f32_16x16x32_bf16 v[106:109], v[122:125], v[142:145], v[106:109]
	v_mfma_f32_16x16x32_bf16 v[94:97], v[114:117], v[162:165], v[94:97]
	v_mfma_f32_16x16x32_bf16 v[90:93], v[122:125], v[162:165], v[90:93]
	v_mfma_f32_16x16x32_bf16 v[78:81], v[114:117], v[174:177], v[78:81]
	v_mfma_f32_16x16x32_bf16 v[74:77], v[122:125], v[174:177], v[74:77]
	v_mfma_f32_16x16x32_bf16 v[158:161], v[126:129], v[138:141], v[146:149]
	v_mfma_f32_16x16x32_bf16 v[110:113], v[118:121], v[154:157], v[110:113]
	v_mfma_f32_16x16x32_bf16 v[106:109], v[126:129], v[154:157], v[106:109]
	v_mfma_f32_16x16x32_bf16 v[94:97], v[118:121], v[170:173], v[94:97]
	v_mfma_f32_16x16x32_bf16 v[90:93], v[126:129], v[170:173], v[90:93]
	v_mfma_f32_16x16x32_bf16 v[78:81], v[118:121], v[186:189], v[78:81]
	v_mfma_f32_16x16x32_bf16 v[74:77], v[126:129], v[186:189], v[74:77]
	s_barrier
	s_add_i32 s14, 0, 0x1c000
	v_add_u32_e32 v146, s14, v216
	s_add_i32 s15, s16, s22
	ds_read_b128 v[190:193], v146
	ds_read_b128 v[194:197], v146 offset:1024
	ds_read_b128 v[206:209], v146 offset:2048
	ds_read_b128 v[210:213], v146 offset:3072
	v_lshl_add_u64 v[146:147], v[200:201], 0, s[78:79]
	s_mov_b32 m0, s15
	s_nop 0
	global_load_lds_dwordx4 v[146:147], off
	v_lshl_add_u64 v[146:147], v[220:221], 0, s[78:79]
	s_add_i32 m0, s15, 0x2000
	s_nop 0
	global_load_lds_dwordx4 v[146:147], off
	s_barrier
	s_waitcnt lgkmcnt(0)
	s_waitcnt lgkmcnt(0)
	v_mfma_f32_16x16x32_bf16 v[146:149], v[190:193], v[134:137], v[150:153]
	v_mfma_f32_16x16x32_bf16 v[130:133], v[206:209], v[134:137], v[130:133]
	v_mfma_f32_16x16x32_bf16 v[102:105], v[190:193], v[142:145], v[102:105]
	v_mfma_f32_16x16x32_bf16 v[98:101], v[206:209], v[142:145], v[98:101]
	v_mfma_f32_16x16x32_bf16 v[86:89], v[190:193], v[162:165], v[86:89]
	v_mfma_f32_16x16x32_bf16 v[82:85], v[206:209], v[162:165], v[82:85]
	v_mfma_f32_16x16x32_bf16 v[70:73], v[190:193], v[174:177], v[70:73]
	v_mfma_f32_16x16x32_bf16 v[66:69], v[206:209], v[174:177], v[66:69]
	v_mfma_f32_16x16x32_bf16 v[150:153], v[194:197], v[138:141], v[146:149]
	v_mfma_f32_16x16x32_bf16 v[146:149], v[210:213], v[138:141], v[130:133]
	v_mfma_f32_16x16x32_bf16 v[102:105], v[194:197], v[154:157], v[102:105]
	v_mfma_f32_16x16x32_bf16 v[98:101], v[210:213], v[154:157], v[98:101]
	v_mfma_f32_16x16x32_bf16 v[86:89], v[194:197], v[170:173], v[86:89]
	v_mfma_f32_16x16x32_bf16 v[82:85], v[210:213], v[170:173], v[82:85]
	v_mfma_f32_16x16x32_bf16 v[70:73], v[194:197], v[186:189], v[70:73]
	v_mfma_f32_16x16x32_bf16 v[66:69], v[210:213], v[186:189], v[66:69]
	s_mov_b32 m0, s28
	v_lshl_add_u64 v[186:187], v[222:223], 0, s[78:79]
	s_barrier
	ds_read_b128 v[130:133], v218 offset:49152
	ds_read_b128 v[134:137], v218 offset:50176
	ds_read_b128 v[138:141], v218 offset:51200
	ds_read_b128 v[142:145], v218 offset:52224
	ds_read_b128 v[154:157], v218 offset:53248
	ds_read_b128 v[162:165], v218 offset:54272
	ds_read_b128 v[170:173], v218 offset:55296
	ds_read_b128 v[174:177], v218 offset:56320
	global_load_lds_dwordx4 v[186:187], off
	v_lshl_add_u64 v[186:187], v[224:225], 0, s[78:79]
	s_mov_b32 m0, s29
	s_nop 0
	global_load_lds_dwordx4 v[186:187], off
	s_barrier
	s_waitcnt lgkmcnt(0)
	s_waitcnt lgkmcnt(0)
	v_mfma_f32_16x16x32_bf16 v[62:65], v[114:117], v[130:133], v[62:65]
	v_mfma_f32_16x16x32_bf16 v[58:61], v[122:125], v[130:133], v[58:61]
	v_mfma_f32_16x16x32_bf16 v[46:49], v[114:117], v[138:141], v[46:49]
	v_mfma_f32_16x16x32_bf16 v[42:45], v[122:125], v[138:141], v[42:45]
	v_mfma_f32_16x16x32_bf16 v[30:33], v[114:117], v[154:157], v[30:33]
	v_mfma_f32_16x16x32_bf16 v[26:29], v[122:125], v[154:157], v[26:29]
	v_mfma_f32_16x16x32_bf16 v[14:17], v[114:117], v[170:173], v[14:17]
	v_mfma_f32_16x16x32_bf16 v[10:13], v[122:125], v[170:173], v[10:13]
	v_mfma_f32_16x16x32_bf16 v[62:65], v[118:121], v[134:137], v[62:65]
	v_mfma_f32_16x16x32_bf16 v[58:61], v[126:129], v[134:137], v[58:61]
	v_mfma_f32_16x16x32_bf16 v[46:49], v[118:121], v[142:145], v[46:49]
	v_mfma_f32_16x16x32_bf16 v[42:45], v[126:129], v[142:145], v[42:45]
	v_mfma_f32_16x16x32_bf16 v[30:33], v[118:121], v[162:165], v[30:33]
	v_mfma_f32_16x16x32_bf16 v[26:29], v[126:129], v[162:165], v[26:29]
	v_mfma_f32_16x16x32_bf16 v[14:17], v[118:121], v[174:177], v[14:17]
	v_mfma_f32_16x16x32_bf16 v[10:13], v[126:129], v[174:177], v[10:13]
	s_barrier
	s_add_i32 s14, s14, s22
	v_lshl_add_u64 v[114:115], v[226:227], 0, s[78:79]
	s_mov_b32 m0, s14
	s_nop 0
	global_load_lds_dwordx4 v[114:115], off
	v_lshl_add_u64 v[114:115], v[228:229], 0, s[78:79]
	s_add_i32 m0, s14, 0x2000
	s_nop 0
	global_load_lds_dwordx4 v[114:115], off
	s_waitcnt vmcnt(6)
	s_barrier
	v_mfma_f32_16x16x32_bf16 v[54:57], v[190:193], v[130:133], v[54:57]
	v_mfma_f32_16x16x32_bf16 v[50:53], v[206:209], v[130:133], v[50:53]
	v_mfma_f32_16x16x32_bf16 v[38:41], v[190:193], v[138:141], v[38:41]
	v_mfma_f32_16x16x32_bf16 v[34:37], v[206:209], v[138:141], v[34:37]
	v_mfma_f32_16x16x32_bf16 v[22:25], v[190:193], v[154:157], v[22:25]
	v_mfma_f32_16x16x32_bf16 v[18:21], v[206:209], v[154:157], v[18:21]
	v_mfma_f32_16x16x32_bf16 v[6:9], v[190:193], v[170:173], v[6:9]
	v_mfma_f32_16x16x32_bf16 v[2:5], v[206:209], v[170:173], v[2:5]
	v_mfma_f32_16x16x32_bf16 v[54:57], v[194:197], v[134:137], v[54:57]
	v_mfma_f32_16x16x32_bf16 v[50:53], v[210:213], v[134:137], v[50:53]
	v_mfma_f32_16x16x32_bf16 v[38:41], v[194:197], v[142:145], v[38:41]
	v_mfma_f32_16x16x32_bf16 v[34:37], v[210:213], v[142:145], v[34:37]
	v_mfma_f32_16x16x32_bf16 v[22:25], v[194:197], v[162:165], v[22:25]
	v_mfma_f32_16x16x32_bf16 v[18:21], v[210:213], v[162:165], v[18:21]
	v_mfma_f32_16x16x32_bf16 v[6:9], v[194:197], v[174:177], v[6:9]
	v_mfma_f32_16x16x32_bf16 v[2:5], v[210:213], v[174:177], v[2:5]
	s_add_u32 s12, s12, 0x100
	s_addc_u32 s13, s13, 0
	s_add_u32 s38, s38, 0x100
	s_addc_u32 s39, s39, 0
	s_cmp_ge_u32 s40, s27
	s_mov_b32 s14, s40
	s_barrier
	s_cbranch_scc0 .LBB0_1348
	v_readlane_b32 s100, v254, 20
	s_nop 1
	s_cmp_lg_u32 s100, 3
	s_cselect_b64 s[100:101], -1, 0
	s_and_b64 s[0:1], s[0:1], s[100:101]
	v_lshl_add_u32 v190, s37, 8, v179
	v_lshl_or_b32 v186, s36, 8, v217
	v_ashrrev_i32_e32 v187, 31, v186
	v_ashrrev_i32_e32 v191, 31, v190
	v_lshl_add_u64 v[188:189], v[186:187], 2, s[10:11]
	v_lshlrev_b64 v[114:115], 13, v[190:191]
	v_lshl_add_u64 v[114:115], v[188:189], 0, v[114:115]
	global_load_dwordx4 v[206:209], v[114:115], off
	global_load_dwordx4 v[210:213], v[114:115], off offset:64
	global_load_dwordx4 v[220:223], v[114:115], off offset:512
	global_load_dwordx4 v[224:227], v[114:115], off offset:576
	v_or_b32_e32 v196, 16, v190
	v_ashrrev_i32_e32 v197, 31, v196
	v_lshlrev_b64 v[114:115], 13, v[196:197]
	v_or_b32_e32 v194, 32, v190
	v_lshl_add_u64 v[114:115], v[188:189], 0, v[114:115]
	v_ashrrev_i32_e32 v195, 31, v194
	global_load_dwordx4 v[174:177], v[114:115], off
	global_load_dwordx4 v[170:173], v[114:115], off offset:64
	global_load_dwordx4 v[162:165], v[114:115], off offset:512
	global_load_dwordx4 v[154:157], v[114:115], off offset:576
	v_lshlrev_b64 v[114:115], 13, v[194:195]
	v_or_b32_e32 v192, 48, v190
	v_lshl_add_u64 v[114:115], v[188:189], 0, v[114:115]
	v_ashrrev_i32_e32 v193, 31, v192
	global_load_dwordx4 v[142:145], v[114:115], off
	global_load_dwordx4 v[138:141], v[114:115], off offset:64
	global_load_dwordx4 v[130:133], v[114:115], off offset:512
	global_load_dwordx4 v[122:125], v[114:115], off offset:576
	v_lshlrev_b64 v[114:115], 13, v[192:193]
	v_lshl_add_u64 v[114:115], v[188:189], 0, v[114:115]
	global_load_dwordx4 v[134:137], v[114:115], off
	global_load_dwordx4 v[126:129], v[114:115], off offset:64
	global_load_dwordx4 v[118:121], v[114:115], off offset:512
	s_nop 0
	global_load_dwordx4 v[114:117], v[114:115], off offset:576
	v_lshlrev_b64 v[200:201], 11, v[190:191]
	v_lshl_add_u64 v[200:201], v[200:201], 0, v[186:187]
	v_readlane_b32 s12, v252, 35
	v_readlane_b32 s13, v252, 36
	s_waitcnt vmcnt(0)
	v_pk_add_f32 v[166:167], v[166:167], v[206:207]
	s_nop 0
	v_mul_f32_e32 v199, v167, v167
	v_pk_add_f32 v[168:169], v[168:169], v[208:209]
	v_fmac_f32_e32 v199, v166, v166
	v_lshl_add_u64 v[206:207], v[200:201], 2, s[72:73]
	v_fmac_f32_e32 v199, v168, v168
	global_store_dwordx4 v[206:207], v[166:169], off
	v_fmac_f32_e32 v199, v169, v169
	v_pk_add_f32 v[158:159], v[158:159], v[210:211]
	v_cvt_pk_bf16_f32 v166, v166, v167
	v_cvt_pk_bf16_f32 v167, v168, v169
	v_lshlrev_b64 v[168:169], 1, v[200:201]
	v_lshl_add_u64 v[200:201], s[12:13], 0, v[168:169]
	s_mov_b64 exec, s[100:101]
	global_store_dwordx2 v[200:201], v[166:167], off
	s_mov_b64 exec, -1
	v_mul_f32_e32 v166, v159, v159
	v_pk_add_f32 v[160:161], v[160:161], v[212:213]
	v_fmac_f32_e32 v166, v158, v158
	v_fmac_f32_e32 v166, v160, v160
	global_store_dwordx4 v[206:207], v[158:161], off offset:64
	v_fmac_f32_e32 v166, v161, v161
	v_pk_add_f32 v[150:151], v[150:151], v[220:221]
	v_cvt_pk_bf16_f32 v158, v158, v159
	v_cvt_pk_bf16_f32 v159, v160, v161
	v_or_b32_e32 v160, 32, v168
	v_mov_b32_e32 v161, v169
	v_lshl_add_u64 v[160:161], s[12:13], 0, v[160:161]
	s_mov_b64 exec, s[100:101]
	global_store_dwordx2 v[160:161], v[158:159], off
	s_mov_b64 exec, -1
	v_mul_f32_e32 v158, v151, v151
	v_pk_add_f32 v[152:153], v[152:153], v[222:223]
	v_fmac_f32_e32 v158, v150, v150
	v_fmac_f32_e32 v158, v152, v152
	global_store_dwordx4 v[206:207], v[150:153], off offset:512
	v_fmac_f32_e32 v158, v153, v153
	v_pk_add_f32 v[146:147], v[146:147], v[224:225]
	v_cvt_pk_bf16_f32 v150, v150, v151
	v_cvt_pk_bf16_f32 v151, v152, v153
	v_or_b32_e32 v152, 0x100, v168
	v_mov_b32_e32 v153, v169
	v_lshl_add_u64 v[152:153], s[12:13], 0, v[152:153]
	s_mov_b64 exec, s[100:101]
	global_store_dwordx2 v[152:153], v[150:151], off
	s_mov_b64 exec, -1
	v_mul_f32_e32 v150, v147, v147
	v_pk_add_f32 v[148:149], v[148:149], v[226:227]
	v_fmac_f32_e32 v150, v146, v146
	v_fmac_f32_e32 v150, v148, v148
	v_or_b32_e32 v168, 0x120, v168
	global_store_dwordx4 v[206:207], v[146:149], off offset:576
	v_fmac_f32_e32 v150, v149, v149
	v_add_f32_e32 v166, v199, v166
	v_cvt_pk_bf16_f32 v146, v146, v147
	v_cvt_pk_bf16_f32 v147, v148, v149
	v_lshl_add_u64 v[148:149], s[12:13], 0, v[168:169]
	s_mov_b64 exec, s[100:101]
	global_store_dwordx2 v[148:149], v[146:147], off
	s_mov_b64 exec, -1
	v_and_b32_e32 v147, 64, v205
	v_xor_b32_e32 v146, 16, v205
	v_add_u32_e32 v147, 64, v147
	v_cmp_lt_i32_e32 vcc, v146, v147
	v_add_f32_e32 v158, v166, v158
	v_add_f32_e32 v150, v158, v150
	v_cndmask_b32_e32 v146, v205, v146, vcc
	v_lshlrev_b32_e32 v166, 2, v146
	ds_bpermute_b32 v146, v166, v150
	v_xor_b32_e32 v148, 32, v205
	v_cmp_lt_i32_e32 vcc, v148, v147
	s_waitcnt lgkmcnt(0)
	v_add_f32_e32 v146, v150, v146
	v_cndmask_b32_e32 v147, v205, v148, vcc
	v_lshlrev_b32_e32 v167, 2, v147
	ds_bpermute_b32 v147, v167, v146
	s_and_saveexec_b64 s[12:13], s[0:1]
	s_cbranch_execz .LBB0_1351
	v_readlane_b32 s14, v252, 28
	v_readlane_b32 s15, v252, 29
	s_waitcnt lgkmcnt(0)
	v_add_f32_e32 v146, v146, v147
	v_lshl_add_u64 v[148:149], v[190:191], 2, s[14:15]
	global_atomic_add_f32 v[148:149], v146, off
